# attention unit header: waits for the prefetched first tile no longer count the previous unit's eight O stores (map-0 waves, units 2-4)
# speedup vs baseline: 1.0131x; 1.0131x over previous
.LBB0_276:
	s_or_b32 s46, s9, s79
	s_and_b32 s98, s46, 7
	s_add_i32 s0, s98, 1
	v_cvt_f32_ubyte0_e32 v0, s0
	s_mov_b32 s0, 0x42fc0000
	v_cmp_lt_f32_e32 vcc, s0, v0
	s_and_b64 s[0:1], vcc, exec
	s_cselect_b32 s0, 0xffffffc0, 0
	v_cndmask_b32_e32 v1, 0, v157, vcc
	v_sub_f32_e32 v0, v1, v0
	v_exp_f32_e32 v0, v0
	v_mov_b32_e32 v1, v152
	s_bitcmp0_b32 s9, 0
	v_ldexp_f32 v0, v0, s0
	v_mul_f32_e32 v138, 0x3fb8aa3b, v0
	v_bfe_u32 v0, v1, 3, 1
	v_lshlrev_b32_e32 v169, 3, v1
	v_mul_u32_u24_e32 v9, 0x2400, v0
	v_and_b32_e32 v0, 56, v169
	v_ashrrev_i32_e32 v2, 4, v1
	v_mad_u64_u32 v[4:5], s[34:35], v2, s80, v[0:1]
	v_ashrrev_i32_e32 v10, 3, v1
	v_lshl_add_u32 v175, v4, 1, v9
	v_mul_lo_u32 v4, v10, s80
	v_add_u32_e32 v11, 0x200, v1
	v_add_lshl_u32 v176, v4, v0, 1
	v_ashrrev_i32_e32 v4, 4, v11
	v_mad_u64_u32 v[6:7], s[34:35], v4, s80, v[0:1]
	v_lshl_add_u32 v177, v6, 1, v9
	v_ashrrev_i32_e32 v6, 3, v11
	v_mul_lo_u32 v7, v6, s80
	v_add_lshl_u32 v178, v7, v0, 1
	v_cmp_ne_u32_e64 vcc, s9, 0
	v_lshrrev_b32_e32 v210, 2, v1
	s_nop 1
	v_cndmask_b32_e64 v211, 0, 64, vcc
	v_cmp_lt_u32_e32 vcc, v210, v211
	s_cbranch_vccz .Lat_strict
	v_add_u32_e32 v0, 0, v175
	s_waitcnt vmcnt(11)
	ds_write_b128 v0, v[118:121]
	v_add_u32_e32 v0, 0, v176
	s_waitcnt vmcnt(10)
	ds_write_b128 v0, v[114:117] offset:18432
	v_add_u32_e32 v0, 0, v177
	s_waitcnt vmcnt(9)
	ds_write_b128 v0, v[122:125]
	v_add_u32_e32 v0, 0, v178
	v_lshlrev_b32_e32 v7, 1, v1
	v_lshrrev_b32_e32 v9, 1, v1
	s_waitcnt vmcnt(8)
	ds_write_b128 v0, v[126:129] offset:18432
	s_branch .Lat_join
.Lat_strict:
	v_add_u32_e32 v0, 0, v175
	s_waitcnt vmcnt(3)
	ds_write_b128 v0, v[118:121]
	v_add_u32_e32 v0, 0, v176
	s_waitcnt vmcnt(2)
	ds_write_b128 v0, v[114:117] offset:18432
	v_add_u32_e32 v0, 0, v177
	s_waitcnt vmcnt(1)
	ds_write_b128 v0, v[122:125]
	v_add_u32_e32 v0, 0, v178
	v_lshlrev_b32_e32 v7, 1, v1
	v_lshrrev_b32_e32 v9, 1, v1
	s_waitcnt vmcnt(0)
	ds_write_b128 v0, v[126:129] offset:18432
.Lat_join:
	v_and_b32_e32 v0, 19, v1
	v_and_b32_e32 v7, 8, v7
	v_and_b32_e32 v9, 4, v9
	v_or3_b32 v0, v0, v7, v9
	v_mul_u32_u24_e32 v179, 0x90, v0
	v_and_b32_e32 v0, 7, v1
	v_lshlrev_b32_e32 v96, 4, v0
	v_add_u32_e32 v0, s8, v10
	v_and_b32_e32 v171, 31, v1
	v_readfirstlane_b32 s65, v1
	v_and_b32_e32 v168, 63, v1
	v_bfe_u32 v170, v1, 5, 1
	v_and_b32_e32 v8, 15, v1
	v_ashrrev_i32_e32 v1, 31, v0
	v_lshlrev_b64 v[0:1], 15, v[0:1]
	s_cselect_b64 s[0:1], -1, 0
	v_lshl_add_u64 v[144:145], s[42:43], 0, v[0:1]
	v_add_u32_e32 v0, s8, v6
	s_and_b64 s[34:35], s[0:1], exec
	v_ashrrev_i32_e32 v1, 31, v0
	s_cselect_b32 s38, s77, s78
	s_and_b32 s48, s65, 0x3fffffc0
	v_ashrrev_i32_e32 v3, 31, v2
	v_lshlrev_b64 v[0:1], 15, v[0:1]
	s_lshl_b32 s49, s38, 7
	s_lshl_b32 s34, s48, 2
	v_lshl_add_u64 v[146:147], s[42:43], 0, v[0:1]
	v_lshlrev_b64 v[0:1], 11, v[2:3]
	v_lshlrev_b32_e32 v2, 4, v8
	v_ashrrev_i32_e32 v5, 31, v4
	s_add_i32 s66, s34, 0
	s_or_b32 s34, s49, 0x7f
	v_or_b32_e32 v0, v0, v2
	s_bfe_u32 s64, s65, 0x20006
	v_cvt_f32_u32_e32 v181, s34
	v_lshl_add_u64 v[148:149], s[86:87], 0, v[0:1]
	v_lshlrev_b64 v[0:1], 11, v[4:5]
	s_lshl_b32 s39, s64, 5
	v_or_b32_e32 v0, v0, v2
	v_mov_b32_e32 v14, v97
	v_mov_b32_e32 v15, v97
	s_or_b32 s99, s39, s49
	s_lshl_b32 s69, s38, 1
	s_add_i32 s66, s66, 0x1b000
	v_lshl_add_u64 v[150:151], s[86:87], 0, v[0:1]
	v_mov_b32_e32 v0, v97
	v_mov_b32_e32 v1, v97
	v_mov_b32_e32 v2, v97
	v_mov_b32_e32 v3, v97
	v_mov_b32_e32 v4, v97
	v_mov_b32_e32 v5, v97
	v_mov_b32_e32 v6, v97
	v_mov_b32_e32 v7, v97
	v_mov_b32_e32 v8, v97
	v_mov_b32_e32 v9, v97
	v_mov_b32_e32 v10, v97
	v_mov_b32_e32 v11, v97
	v_mov_b32_e32 v12, v97
	v_mov_b32_e32 v13, v97
	v_mov_b64_e32 v[30:31], v[14:15]
	v_mov_b64_e32 v[46:47], v[14:15]
	v_mov_b64_e32 v[62:63], v[14:15]
	s_mov_b32 s68, 1
	s_ashr_i32 s67, s65, 8
	s_add_i32 s69, s69, 2
	v_lshlrev_b32_e32 v172, 4, v170
	v_mul_u32_u24_e32 v180, 0x90, v171
	s_or_b32 s70, s99, 31
	v_lshlrev_b32_e32 v182, 3, v170
	v_or_b32_e32 v183, s99, v171
	v_cmp_gt_u32_e64 s[38:39], 32, v168
	v_lshl_add_u32 v173, v171, 2, s66
	v_mov_b32_e32 v140, v138
	v_mov_b32_e32 v141, v138
	v_mov_b32_e32 v142, v138
	v_mov_b32_e32 v143, v138
	s_add_i32 s48, s49, 0x80
	v_mov_b32_e32 v174, 0
	s_mov_b32 s49, 0
	v_mov_b64_e32 v[28:29], v[12:13]
	v_mov_b64_e32 v[26:27], v[10:11]
	v_mov_b64_e32 v[24:25], v[8:9]
	v_mov_b64_e32 v[22:23], v[6:7]
	v_mov_b64_e32 v[20:21], v[4:5]
	v_mov_b64_e32 v[18:19], v[2:3]
	v_mov_b64_e32 v[16:17], v[0:1]
	v_mov_b64_e32 v[44:45], v[12:13]
	v_mov_b64_e32 v[42:43], v[10:11]
	v_mov_b64_e32 v[40:41], v[8:9]
	v_mov_b64_e32 v[38:39], v[6:7]
	v_mov_b64_e32 v[36:37], v[4:5]
	v_mov_b64_e32 v[34:35], v[2:3]
	v_mov_b64_e32 v[32:33], v[0:1]
	v_mov_b64_e32 v[60:61], v[12:13]
	v_mov_b64_e32 v[58:59], v[10:11]
	v_mov_b64_e32 v[56:57], v[8:9]
	v_mov_b64_e32 v[54:55], v[6:7]
	v_mov_b64_e32 v[52:53], v[4:5]
	v_mov_b64_e32 v[50:51], v[2:3]
	v_mov_b64_e32 v[48:49], v[0:1]
	s_mov_b32 s50, 0
	v_mov_b32_e32 v184, 0
	s_waitcnt lgkmcnt(0)
	s_barrier
	s_branch .LBB0_278
